# hosted table-quant L2 touch-ahead distance 4 rows (was 2)
# speedup vs baseline: 1.0046x; 1.0015x over previous
; __device__ void quant_rows(const float* src, unsigned char* dst, float* scales, int row_begin, int nrows) {
;     ...
;   for (int row = row_begin + blockIdx.x * 4 + w; row < nrows; row += gridDim.x * 4) {
;     const f32x4* sp = (const f32x4*)(src + (size_t)row * 1024) + lane * 4;
;     f32x4 v[4];
;     float am = 0.f;
; #pragma unroll
;     for (int k = 0; k < 4; ++k) {
;       v[k] = sp[k];
;       am = fmaxf(am, fmaxf(fmaxf(fabsf(v[k].x), fabsf(v[k].y)), fmaxf(fabsf(v[k].z), fabsf(v[k].w))));
;     }
;     am = fmaxf(am, __shfl_xor(am, 1)); am = fmaxf(am, __shfl_xor(am, 2)); am = fmaxf(am, __shfl_xor(am, 4));
;     am = fmaxf(am, __shfl_xor(am, 8)); am = fmaxf(am, __shfl_xor(am, 16)); am = fmaxf(am, __shfl_xor(am, 32));
;     const float sc = am > 0.f ? 6.f / am : 1.f;
;     u32x2 o;
; #pragma unroll
;     for (int k = 0; k < 2; ++k) {
;       unsigned wd = 0u;
;       wd = __builtin_amdgcn_cvt_scalef32_pk_fp4_f32(wd, v[2 * k].x * sc, v[2 * k].y * sc, 1.0f, 0);
;       wd = __builtin_amdgcn_cvt_scalef32_pk_fp4_f32(wd, v[2 * k].z * sc, v[2 * k].w * sc, 1.0f, 1);
;       wd = __builtin_amdgcn_cvt_scalef32_pk_fp4_f32(wd, v[2 * k + 1].x * sc, v[2 * k + 1].y * sc, 1.0f, 2);
;       wd = __builtin_amdgcn_cvt_scalef32_pk_fp4_f32(wd, v[2 * k + 1].z * sc, v[2 * k + 1].w * sc, 1.0f, 3);
;       o[k] = wd;
;     }
;     ((u32x2*)(dst + (size_t)row * 512))[lane] = o;
;     if (lane == 0) scales[row] = am > 0.f ? am * (1.f / 6.f) : 1.f;
;   }
.LBB0_443:
	v_ashrrev_i32_e32 v3, 31, v2
	v_lshlrev_b64 v[30:31], 12, v[2:3]
	s_waitcnt vmcnt(14)
	v_lshl_add_u64 v[42:43], v[20:21], 0, v[30:31]
	s_mul_i32 s57, s86, 4
	v_add_u32_e32 v200, s57, v2
	v_cmp_gt_i32_e32 vcc, s19, v200
	s_lshl_b32 s57, s57, 12
	v_mov_b32_e32 v200, s57
	v_cndmask_b32_e32 v200, 0, v200, vcc
	v_add_co_u32_e32 v194, vcc, v200, v42
	s_nop 1
	v_addc_co_u32_e32 v195, vcc, 0, v43, vcc
	global_load_dwordx4 v[30:33], v[42:43], off
	global_load_dwordx4 v[34:37], v[42:43], off offset:16
	global_load_dwordx4 v[38:41], v[42:43], off offset:32
	s_nop 0
	global_load_dwordx4 v[42:45], v[42:43], off offset:48
	global_load_dwordx4 v[196:199], v[194:195], off
	global_load_dwordx4 v[196:199], v[194:195], off offset:16
	global_load_dwordx4 v[196:199], v[194:195], off offset:32
	global_load_dwordx4 v[196:199], v[194:195], off offset:48
	s_mov_b32 s23, 0x40c00000
	s_waitcnt vmcnt(7)
	v_max_f32_e64 v0, |v33|, |v33|
	v_max_f32_e64 v46, |v32|, |v32|
	s_waitcnt vmcnt(6)
	v_max_f32_e64 v47, |v37|, |v37|
	v_max_f32_e64 v48, |v36|, |v36|
	s_waitcnt vmcnt(5)
	v_max_f32_e64 v49, |v41|, |v41|
	v_max_f32_e64 v50, |v40|, |v40|
	s_waitcnt vmcnt(4)
	v_max_f32_e64 v51, |v45|, |v45|
	v_max_f32_e64 v52, |v44|, |v44|
	v_max_f32_e32 v0, v46, v0
	v_max_f32_e32 v46, v48, v47
	v_max_f32_e32 v47, v50, v49
	v_max_f32_e32 v48, v52, v51
	v_max3_f32 v0, |v30|, |v31|, v0
	v_max3_f32 v46, |v34|, |v35|, v46
	v_max3_f32 v47, |v38|, |v39|, v47
	v_max3_f32 v48, |v42|, |v43|, v48
	v_max3_f32 v0, v0, 0, v46
	v_max3_f32 v0, v0, v47, v48
	ds_bpermute_b32 v46, v24, v0
	v_mov_b32_e32 v47, v1
	s_waitcnt lgkmcnt(0)
	v_max_f32_e32 v46, v46, v46
	v_max_f32_e32 v0, v0, v46
	ds_bpermute_b32 v46, v25, v0
	s_waitcnt lgkmcnt(0)
	v_max_f32_e32 v46, v46, v46
	v_max_f32_e32 v0, v0, v46
	ds_bpermute_b32 v46, v26, v0
	s_waitcnt lgkmcnt(0)
	v_max_f32_e32 v46, v46, v46
	v_max_f32_e32 v0, v0, v46
	ds_bpermute_b32 v46, v27, v0
	s_waitcnt lgkmcnt(0)
	v_max_f32_e32 v46, v46, v46
	v_max_f32_e32 v0, v0, v46
	ds_bpermute_b32 v46, v28, v0
	s_waitcnt lgkmcnt(0)
	v_max_f32_e32 v46, v46, v46
	v_max_f32_e32 v0, v0, v46
	ds_bpermute_b32 v48, v29, v0
	v_mov_b32_e32 v46, v1
	s_waitcnt lgkmcnt(0)
	v_max_f32_e32 v48, v48, v48
	v_max_f32_e32 v0, v0, v48
	v_div_scale_f32 v50, s[20:21], v0, v0, s23
	v_rcp_f32_e32 v51, v50
	v_div_scale_f32 v52, vcc, s23, v0, s23
	v_lshlrev_b64 v[48:49], 9, v[2:3]
	v_fma_f32 v53, -v50, v51, 1.0
	v_fmac_f32_e32 v51, v53, v51
	v_mul_f32_e32 v53, v52, v51
	v_fma_f32 v54, -v50, v53, v52
	v_fmac_f32_e32 v53, v54, v51
	v_fma_f32 v50, -v50, v53, v52
	v_div_fmas_f32 v50, v50, v51, v53
	v_div_fixup_f32 v50, v50, v0, s23
	v_cmp_lt_f32_e32 vcc, 0, v0
	s_nop 1
	v_cndmask_b32_e32 v50, 1.0, v50, vcc
	v_mul_f32_e32 v30, v30, v50
	v_mul_f32_e32 v31, v31, v50
	v_mul_f32_e32 v38, v38, v50
	v_mul_f32_e32 v39, v39, v50
	v_mul_f32_e32 v32, v32, v50
	v_mul_f32_e32 v33, v33, v50
	v_mul_f32_e32 v40, v40, v50
	v_mul_f32_e32 v41, v41, v50
	v_cvt_scalef32_pk_fp4_f32 v46, v30, v31, 1.0
	v_cvt_scalef32_pk_fp4_f32 v47, v38, v39, 1.0
	v_mul_f32_e32 v34, v34, v50
	v_mul_f32_e32 v35, v35, v50
	v_mul_f32_e32 v42, v42, v50
	v_mul_f32_e32 v43, v43, v50
	v_cvt_scalef32_pk_fp4_f32 v46, v32, v33, 1.0 op_sel:[0,0,1,0]
	v_cvt_scalef32_pk_fp4_f32 v47, v40, v41, 1.0 op_sel:[0,0,1,0]
	v_mul_f32_e32 v36, v36, v50
	v_mul_f32_e32 v37, v37, v50
	v_mul_f32_e32 v44, v44, v50
	v_mul_f32_e32 v45, v45, v50
	v_cvt_scalef32_pk_fp4_f32 v46, v34, v35, 1.0 op_sel:[0,0,0,1]
	v_cvt_scalef32_pk_fp4_f32 v47, v42, v43, 1.0 op_sel:[0,0,0,1]
	v_cvt_scalef32_pk_fp4_f32 v46, v36, v37, 1.0 op_sel:[0,0,1,1]
	v_cvt_scalef32_pk_fp4_f32 v47, v44, v45, 1.0 op_sel:[0,0,1,1]
	v_lshl_add_u64 v[30:31], v[22:23], 0, v[48:49]
	global_store_dwordx2 v[30:31], v[46:47], off
	s_and_saveexec_b64 s[20:21], s[0:1]
	s_cbranch_execz .LBB0_442
	v_mul_f32_e32 v0, 0x3e2aaaab, v0
	v_cndmask_b32_e32 v0, 1.0, v0, vcc
	v_lshl_add_u64 v[30:31], v[2:3], 2, s[8:9]
	global_store_dword v[30:31], v0, off
	s_branch .LBB0_442

; __device__ void quant_rows(const float* src, unsigned char* dst, float* scales, int row_begin, int nrows) {
;     ...
;   for (int row = row_begin + blockIdx.x * 4 + w; row < nrows; row += gridDim.x * 4) {
;     const f32x4* sp = (const f32x4*)(src + (size_t)row * 1024) + lane * 4;
;     f32x4 v[4];
;     float am = 0.f;
; #pragma unroll
;     for (int k = 0; k < 4; ++k) {
;       v[k] = sp[k];
;       am = fmaxf(am, fmaxf(fmaxf(fabsf(v[k].x), fabsf(v[k].y)), fmaxf(fabsf(v[k].z), fabsf(v[k].w))));
;     }
;     am = fmaxf(am, __shfl_xor(am, 1)); am = fmaxf(am, __shfl_xor(am, 2)); am = fmaxf(am, __shfl_xor(am, 4));
;     am = fmaxf(am, __shfl_xor(am, 8)); am = fmaxf(am, __shfl_xor(am, 16)); am = fmaxf(am, __shfl_xor(am, 32));
;     const float sc = am > 0.f ? 6.f / am : 1.f;
;     u32x2 o;
; #pragma unroll
;     for (int k = 0; k < 2; ++k) {
;       unsigned wd = 0u;
;       wd = __builtin_amdgcn_cvt_scalef32_pk_fp4_f32(wd, v[2 * k].x * sc, v[2 * k].y * sc, 1.0f, 0);
;       wd = __builtin_amdgcn_cvt_scalef32_pk_fp4_f32(wd, v[2 * k].z * sc, v[2 * k].w * sc, 1.0f, 1);
;       wd = __builtin_amdgcn_cvt_scalef32_pk_fp4_f32(wd, v[2 * k + 1].x * sc, v[2 * k + 1].y * sc, 1.0f, 2);
;       wd = __builtin_amdgcn_cvt_scalef32_pk_fp4_f32(wd, v[2 * k + 1].z * sc, v[2 * k + 1].w * sc, 1.0f, 3);
;       o[k] = wd;
;     }
;     ((u32x2*)(dst + (size_t)row * 512))[lane] = o;
;     if (lane == 0) scales[row] = am > 0.f ? am * (1.f / 6.f) : 1.f;
;   }
.LBB0_448:
	v_ashrrev_i32_e32 v3, 31, v2
	v_lshlrev_b64 v[30:31], 12, v[2:3]
	s_waitcnt vmcnt(14)
	v_lshl_add_u64 v[42:43], v[20:21], 0, v[30:31]
	s_mul_i32 s57, s86, 4
	v_add_u32_e32 v200, s57, v2
	v_cmp_gt_i32_e32 vcc, s19, v200
	s_lshl_b32 s57, s57, 12
	v_mov_b32_e32 v200, s57
	v_cndmask_b32_e32 v200, 0, v200, vcc
	v_add_co_u32_e32 v194, vcc, v200, v42
	s_nop 1
	v_addc_co_u32_e32 v195, vcc, 0, v43, vcc
	global_load_dwordx4 v[30:33], v[42:43], off
	global_load_dwordx4 v[34:37], v[42:43], off offset:16
	global_load_dwordx4 v[38:41], v[42:43], off offset:32
	s_nop 0
	global_load_dwordx4 v[42:45], v[42:43], off offset:48
	global_load_dwordx4 v[196:199], v[194:195], off
	global_load_dwordx4 v[196:199], v[194:195], off offset:16
	global_load_dwordx4 v[196:199], v[194:195], off offset:32
	global_load_dwordx4 v[196:199], v[194:195], off offset:48
	s_mov_b32 s22, 0x40c00000
	s_waitcnt vmcnt(7)
	v_max_f32_e64 v0, |v33|, |v33|
	v_max_f32_e64 v46, |v32|, |v32|
	s_waitcnt vmcnt(6)
	v_max_f32_e64 v47, |v37|, |v37|
	v_max_f32_e64 v48, |v36|, |v36|
	s_waitcnt vmcnt(5)
	v_max_f32_e64 v49, |v41|, |v41|
	v_max_f32_e64 v50, |v40|, |v40|
	s_waitcnt vmcnt(4)
	v_max_f32_e64 v51, |v45|, |v45|
	v_max_f32_e64 v52, |v44|, |v44|
	v_max_f32_e32 v0, v46, v0
	v_max_f32_e32 v46, v48, v47
	v_max_f32_e32 v47, v50, v49
	v_max_f32_e32 v48, v52, v51
	v_max3_f32 v0, |v30|, |v31|, v0
	v_max3_f32 v46, |v34|, |v35|, v46
	v_max3_f32 v47, |v38|, |v39|, v47
	v_max3_f32 v48, |v42|, |v43|, v48
	v_max3_f32 v0, v0, 0, v46
	v_max3_f32 v0, v0, v47, v48
	ds_bpermute_b32 v46, v24, v0
	v_mov_b32_e32 v47, v1
	s_waitcnt lgkmcnt(0)
	v_max_f32_e32 v46, v46, v46
	v_max_f32_e32 v0, v0, v46
	ds_bpermute_b32 v46, v25, v0
	s_waitcnt lgkmcnt(0)
	v_max_f32_e32 v46, v46, v46
	v_max_f32_e32 v0, v0, v46
	ds_bpermute_b32 v46, v26, v0
	s_waitcnt lgkmcnt(0)
	v_max_f32_e32 v46, v46, v46
	v_max_f32_e32 v0, v0, v46
	ds_bpermute_b32 v46, v27, v0
	s_waitcnt lgkmcnt(0)
	v_max_f32_e32 v46, v46, v46
	v_max_f32_e32 v0, v0, v46
	ds_bpermute_b32 v46, v28, v0
	s_waitcnt lgkmcnt(0)
	v_max_f32_e32 v46, v46, v46
	v_max_f32_e32 v0, v0, v46
	ds_bpermute_b32 v48, v29, v0
	v_mov_b32_e32 v46, v1
	s_waitcnt lgkmcnt(0)
	v_max_f32_e32 v48, v48, v48
	v_max_f32_e32 v0, v0, v48
	v_div_scale_f32 v50, s[20:21], v0, v0, s22
	v_rcp_f32_e32 v51, v50
	v_div_scale_f32 v52, vcc, s22, v0, s22
	v_lshlrev_b64 v[48:49], 9, v[2:3]
	v_fma_f32 v53, -v50, v51, 1.0
	v_fmac_f32_e32 v51, v53, v51
	v_mul_f32_e32 v53, v52, v51
	v_fma_f32 v54, -v50, v53, v52
	v_fmac_f32_e32 v53, v54, v51
	v_fma_f32 v50, -v50, v53, v52
	v_div_fmas_f32 v50, v50, v51, v53
	v_div_fixup_f32 v50, v50, v0, s22
	v_cmp_lt_f32_e32 vcc, 0, v0
	s_nop 1
	v_cndmask_b32_e32 v50, 1.0, v50, vcc
	v_mul_f32_e32 v30, v30, v50
	v_mul_f32_e32 v31, v31, v50
	v_mul_f32_e32 v38, v38, v50
	v_mul_f32_e32 v39, v39, v50
	v_mul_f32_e32 v32, v32, v50
	v_mul_f32_e32 v33, v33, v50
	v_mul_f32_e32 v40, v40, v50
	v_mul_f32_e32 v41, v41, v50
	v_cvt_scalef32_pk_fp4_f32 v46, v30, v31, 1.0
	v_cvt_scalef32_pk_fp4_f32 v47, v38, v39, 1.0
	v_mul_f32_e32 v34, v34, v50
	v_mul_f32_e32 v35, v35, v50
	v_mul_f32_e32 v42, v42, v50
	v_mul_f32_e32 v43, v43, v50
	v_cvt_scalef32_pk_fp4_f32 v46, v32, v33, 1.0 op_sel:[0,0,1,0]
	v_cvt_scalef32_pk_fp4_f32 v47, v40, v41, 1.0 op_sel:[0,0,1,0]
	v_mul_f32_e32 v36, v36, v50
	v_mul_f32_e32 v37, v37, v50
	v_mul_f32_e32 v44, v44, v50
	v_mul_f32_e32 v45, v45, v50
	v_cvt_scalef32_pk_fp4_f32 v46, v34, v35, 1.0 op_sel:[0,0,0,1]
	v_cvt_scalef32_pk_fp4_f32 v47, v42, v43, 1.0 op_sel:[0,0,0,1]
	v_cvt_scalef32_pk_fp4_f32 v46, v36, v37, 1.0 op_sel:[0,0,1,1]
	v_cvt_scalef32_pk_fp4_f32 v47, v44, v45, 1.0 op_sel:[0,0,1,1]
	v_lshl_add_u64 v[30:31], v[22:23], 0, v[48:49]
	global_store_dwordx2 v[30:31], v[46:47], off
	s_and_saveexec_b64 s[20:21], s[0:1]
	s_cbranch_execz .LBB0_447
	v_mul_f32_e32 v0, 0x3e2aaaab, v0
	v_cndmask_b32_e32 v0, 1.0, v0, vcc
	v_lshl_add_u64 v[30:31], v[2:3], 2, s[8:9]
	global_store_dword v[30:31], v0, off
	s_branch .LBB0_447

; __device__ void quant_rows(const float* src, unsigned char* dst, float* scales, int row_begin, int nrows) {
;     ...
;   for (int row = row_begin + blockIdx.x * 4 + w; row < nrows; row += gridDim.x * 4) {
;     const f32x4* sp = (const f32x4*)(src + (size_t)row * 1024) + lane * 4;
;     f32x4 v[4];
;     float am = 0.f;
; #pragma unroll
;     for (int k = 0; k < 4; ++k) {
;       v[k] = sp[k];
;       am = fmaxf(am, fmaxf(fmaxf(fabsf(v[k].x), fabsf(v[k].y)), fmaxf(fabsf(v[k].z), fabsf(v[k].w))));
;     }
;     am = fmaxf(am, __shfl_xor(am, 1)); am = fmaxf(am, __shfl_xor(am, 2)); am = fmaxf(am, __shfl_xor(am, 4));
;     am = fmaxf(am, __shfl_xor(am, 8)); am = fmaxf(am, __shfl_xor(am, 16)); am = fmaxf(am, __shfl_xor(am, 32));
;     const float sc = am > 0.f ? 6.f / am : 1.f;
;     u32x2 o;
; #pragma unroll
;     for (int k = 0; k < 2; ++k) {
;       unsigned wd = 0u;
;       wd = __builtin_amdgcn_cvt_scalef32_pk_fp4_f32(wd, v[2 * k].x * sc, v[2 * k].y * sc, 1.0f, 0);
;       wd = __builtin_amdgcn_cvt_scalef32_pk_fp4_f32(wd, v[2 * k].z * sc, v[2 * k].w * sc, 1.0f, 1);
;       wd = __builtin_amdgcn_cvt_scalef32_pk_fp4_f32(wd, v[2 * k + 1].x * sc, v[2 * k + 1].y * sc, 1.0f, 2);
;       wd = __builtin_amdgcn_cvt_scalef32_pk_fp4_f32(wd, v[2 * k + 1].z * sc, v[2 * k + 1].w * sc, 1.0f, 3);
;       o[k] = wd;
;     }
;     ((u32x2*)(dst + (size_t)row * 512))[lane] = o;
;     if (lane == 0) scales[row] = am > 0.f ? am * (1.f / 6.f) : 1.f;
;   }
.LBB0_641:
	v_ashrrev_i32_e32 v3, 31, v2
	v_lshlrev_b64 v[30:31], 12, v[2:3]
	s_waitcnt vmcnt(14)
	v_lshl_add_u64 v[42:43], v[20:21], 0, v[30:31]
	s_mul_i32 s57, s86, 4
	v_add_u32_e32 v200, s57, v2
	v_cmp_gt_i32_e32 vcc, s19, v200
	s_lshl_b32 s57, s57, 12
	v_mov_b32_e32 v200, s57
	v_cndmask_b32_e32 v200, 0, v200, vcc
	v_add_co_u32_e32 v194, vcc, v200, v42
	s_nop 1
	v_addc_co_u32_e32 v195, vcc, 0, v43, vcc
	global_load_dwordx4 v[30:33], v[42:43], off
	global_load_dwordx4 v[34:37], v[42:43], off offset:16
	global_load_dwordx4 v[38:41], v[42:43], off offset:32
	s_nop 0
	global_load_dwordx4 v[42:45], v[42:43], off offset:48
	global_load_dwordx4 v[196:199], v[194:195], off
	global_load_dwordx4 v[196:199], v[194:195], off offset:16
	global_load_dwordx4 v[196:199], v[194:195], off offset:32
	global_load_dwordx4 v[196:199], v[194:195], off offset:48
	s_mov_b32 s24, 0x40c00000
	s_waitcnt vmcnt(7)
	v_max_f32_e64 v0, |v33|, |v33|
	v_max_f32_e64 v46, |v32|, |v32|
	s_waitcnt vmcnt(6)
	v_max_f32_e64 v47, |v37|, |v37|
	v_max_f32_e64 v48, |v36|, |v36|
	s_waitcnt vmcnt(5)
	v_max_f32_e64 v49, |v41|, |v41|
	v_max_f32_e64 v50, |v40|, |v40|
	s_waitcnt vmcnt(4)
	v_max_f32_e64 v51, |v45|, |v45|
	v_max_f32_e64 v52, |v44|, |v44|
	v_max_f32_e32 v0, v46, v0
	v_max_f32_e32 v46, v48, v47
	v_max_f32_e32 v47, v50, v49
	v_max_f32_e32 v48, v52, v51
	v_max3_f32 v0, |v30|, |v31|, v0
	v_max3_f32 v46, |v34|, |v35|, v46
	v_max3_f32 v47, |v38|, |v39|, v47
	v_max3_f32 v48, |v42|, |v43|, v48
	v_max3_f32 v0, v0, 0, v46
	v_max3_f32 v0, v0, v47, v48
	ds_bpermute_b32 v46, v24, v0
	v_mov_b32_e32 v47, v1
	s_waitcnt lgkmcnt(0)
	v_max_f32_e32 v46, v46, v46
	v_max_f32_e32 v0, v0, v46
	ds_bpermute_b32 v46, v25, v0
	s_waitcnt lgkmcnt(0)
	v_max_f32_e32 v46, v46, v46
	v_max_f32_e32 v0, v0, v46
	ds_bpermute_b32 v46, v26, v0
	s_waitcnt lgkmcnt(0)
	v_max_f32_e32 v46, v46, v46
	v_max_f32_e32 v0, v0, v46
	ds_bpermute_b32 v46, v27, v0
	s_waitcnt lgkmcnt(0)
	v_max_f32_e32 v46, v46, v46
	v_max_f32_e32 v0, v0, v46
	ds_bpermute_b32 v46, v28, v0
	s_waitcnt lgkmcnt(0)
	v_max_f32_e32 v46, v46, v46
	v_max_f32_e32 v0, v0, v46
	ds_bpermute_b32 v48, v29, v0
	v_mov_b32_e32 v46, v1
	s_waitcnt lgkmcnt(0)
	v_max_f32_e32 v48, v48, v48
	v_max_f32_e32 v0, v0, v48
	v_div_scale_f32 v50, s[22:23], v0, v0, s24
	v_rcp_f32_e32 v51, v50
	v_div_scale_f32 v52, vcc, s24, v0, s24
	v_lshlrev_b64 v[48:49], 9, v[2:3]
	v_fma_f32 v53, -v50, v51, 1.0
	v_fmac_f32_e32 v51, v53, v51
	v_mul_f32_e32 v53, v52, v51
	v_fma_f32 v54, -v50, v53, v52
	v_fmac_f32_e32 v53, v54, v51
	v_fma_f32 v50, -v50, v53, v52
	v_div_fmas_f32 v50, v50, v51, v53
	v_div_fixup_f32 v50, v50, v0, s24
	v_cmp_lt_f32_e32 vcc, 0, v0
	s_nop 1
	v_cndmask_b32_e32 v50, 1.0, v50, vcc
	v_mul_f32_e32 v30, v30, v50
	v_mul_f32_e32 v31, v31, v50
	v_mul_f32_e32 v38, v38, v50
	v_mul_f32_e32 v39, v39, v50
	v_mul_f32_e32 v32, v32, v50
	v_mul_f32_e32 v33, v33, v50
	v_mul_f32_e32 v40, v40, v50
	v_mul_f32_e32 v41, v41, v50
	v_cvt_scalef32_pk_fp4_f32 v46, v30, v31, 1.0
	v_cvt_scalef32_pk_fp4_f32 v47, v38, v39, 1.0
	v_mul_f32_e32 v34, v34, v50
	v_mul_f32_e32 v35, v35, v50
	v_mul_f32_e32 v42, v42, v50
	v_mul_f32_e32 v43, v43, v50
	v_cvt_scalef32_pk_fp4_f32 v46, v32, v33, 1.0 op_sel:[0,0,1,0]
	v_cvt_scalef32_pk_fp4_f32 v47, v40, v41, 1.0 op_sel:[0,0,1,0]
	v_mul_f32_e32 v36, v36, v50
	v_mul_f32_e32 v37, v37, v50
	v_mul_f32_e32 v44, v44, v50
	v_mul_f32_e32 v45, v45, v50
	v_cvt_scalef32_pk_fp4_f32 v46, v34, v35, 1.0 op_sel:[0,0,0,1]
	v_cvt_scalef32_pk_fp4_f32 v47, v42, v43, 1.0 op_sel:[0,0,0,1]
	v_cvt_scalef32_pk_fp4_f32 v46, v36, v37, 1.0 op_sel:[0,0,1,1]
	v_cvt_scalef32_pk_fp4_f32 v47, v44, v45, 1.0 op_sel:[0,0,1,1]
	v_lshl_add_u64 v[30:31], v[22:23], 0, v[48:49]
	global_store_dwordx2 v[30:31], v[46:47], off
	s_and_saveexec_b64 s[22:23], s[0:1]
	s_cbranch_execz .LBB0_640
	v_mul_f32_e32 v0, 0x3e2aaaab, v0
	v_cndmask_b32_e32 v0, 1.0, v0, vcc
	v_lshl_add_u64 v[30:31], v[2:3], 2, s[8:9]
	global_store_dword v[30:31], v0, off
	s_branch .LBB0_640
